# nt hint on the EpiRes residual loads (on top of v5)
# baseline (speedup 1.0000x reference)
.LBB0_1025:
	s_sub_i32 s0, s13, 64
	s_ashr_i32 s1, s13, 31
	s_cmp_lt_i32 s13, 64
	s_cselect_b32 s1, s1, 0
	s_cselect_b32 s0, s13, s0
	s_movk_i32 s5, 0x4800
	s_cselect_b32 s2, s79, s97
	s_cselect_b32 s3, s78, s96
	s_cselect_b32 s5, 0x2400, s5
	s_lshl_b64 s[0:1], s[0:1], 20
	s_add_u32 s0, s3, s0
	s_addc_u32 s1, s2, s1
	s_cmp_gt_i32 s13, 31
	s_cselect_b32 s2, s5, 0
	s_lshl_b32 s2, s2, 2
	v_readlane_b32 s3, v254, 45
	v_lshl_or_b32 v152, s12, 8, v157
	s_add_u32 s2, s3, s2
	v_readlane_b32 s3, v254, 47
	v_ashrrev_i32_e32 v153, 31, v152
	s_addc_u32 s3, s3, 0
	v_lshlrev_b64 v[152:153], 2, v[152:153]
	v_add_u32_e32 v154, 0x5000, v152
	global_load_dwordx4 v[160:163], v154, s[2:3]
	global_load_dwordx4 v[164:167], v154, s[2:3] offset:64
	global_load_dwordx4 v[168:171], v154, s[2:3] offset:512
	global_load_dwordx4 v[172:175], v154, s[2:3] offset:576
	v_add_u32_e32 v159, v152, v132
	v_add_u32_e32 v153, v152, v136
	v_add_u32_e32 v196, v152, v138
	v_add_u32_e32 v197, v152, v140
	v_add_u32_e32 v234, v152, v134
	v_add_u32_e32 v235, v152, v142
	v_add_u32_e32 v210, v152, v144
	v_add_u32_e32 v211, v152, v146
	global_load_dwordx4 v[176:179], v159, s[0:1] nt
	global_load_dwordx4 v[180:183], v153, s[0:1] nt
	global_load_dwordx4 v[184:187], v196, s[0:1] nt
	global_load_dwordx4 v[188:191], v197, s[0:1] nt
	global_load_dwordx4 v[192:195], v234, s[0:1] nt
	global_load_dwordx4 v[214:217], v235, s[0:1] nt
	global_load_dwordx4 v[218:221], v210, s[0:1] nt
	global_load_dwordx4 v[222:225], v211, s[0:1] nt
	global_load_dwordx4 v[226:229], v159, s[0:1] offset:64 nt
	global_load_dwordx4 v[230:233], v153, s[0:1] offset:64 nt
	global_load_dwordx4 v[240:243], v196, s[0:1] offset:64 nt
	global_load_dwordx4 v[244:247], v197, s[0:1] offset:64 nt
	v_readlane_b32 s18, v249, 56
	s_mov_b64 s[2:3], -1
	s_andn2_b64 vcc, exec, s[38:39]
	v_readlane_b32 s19, v249, 57
	s_waitcnt vmcnt(11)
	v_pk_fma_f32 v[128:129], v[128:129], v[162:163], v[178:179]
	v_pk_fma_f32 v[126:127], v[126:127], v[160:161], v[176:177]
	global_store_dwordx4 v159, v[126:129], s[0:1]
	s_nop 1
	global_load_dwordx4 v[126:129], v234, s[0:1] offset:64 nt
	s_waitcnt vmcnt(12)
	v_pk_fma_f32 v[124:125], v[124:125], v[162:163], v[182:183]
	v_pk_fma_f32 v[122:123], v[122:123], v[160:161], v[180:181]
	global_store_dwordx4 v153, v[122:125], s[0:1]
	s_nop 1
	global_load_dwordx4 v[122:125], v235, s[0:1] offset:64 nt
	s_waitcnt vmcnt(13)
	v_pk_fma_f32 v[120:121], v[120:121], v[162:163], v[186:187]
	v_pk_fma_f32 v[118:119], v[118:119], v[160:161], v[184:185]
	global_store_dwordx4 v196, v[118:121], s[0:1]
	s_nop 1
	global_load_dwordx4 v[118:121], v210, s[0:1] offset:64 nt
	s_waitcnt vmcnt(14)
	v_pk_fma_f32 v[116:117], v[116:117], v[162:163], v[190:191]
	v_pk_fma_f32 v[114:115], v[114:115], v[160:161], v[188:189]
	global_store_dwordx4 v197, v[114:117], s[0:1]
	s_nop 1
	global_load_dwordx4 v[114:117], v211, s[0:1] offset:64 nt
	s_waitcnt vmcnt(15)
	v_pk_fma_f32 v[112:113], v[112:113], v[162:163], v[194:195]
	v_pk_fma_f32 v[110:111], v[110:111], v[160:161], v[192:193]
	global_store_dwordx4 v234, v[110:113], s[0:1]
	s_nop 1
	global_load_dwordx4 v[110:113], v159, s[0:1] offset:512 nt
	s_waitcnt vmcnt(16)
	v_pk_fma_f32 v[108:109], v[108:109], v[162:163], v[216:217]
	v_pk_fma_f32 v[106:107], v[106:107], v[160:161], v[214:215]
	global_store_dwordx4 v235, v[106:109], s[0:1]
	s_nop 1
	global_load_dwordx4 v[106:109], v153, s[0:1] offset:512 nt
	s_waitcnt vmcnt(17)
	v_pk_fma_f32 v[100:101], v[100:101], v[162:163], v[220:221]
	v_pk_fma_f32 v[98:99], v[98:99], v[160:161], v[218:219]
	global_store_dwordx4 v210, v[98:101], s[0:1]
	s_nop 1
	global_load_dwordx4 v[98:101], v196, s[0:1] offset:512 nt
	s_waitcnt vmcnt(18)
	v_pk_fma_f32 v[96:97], v[96:97], v[162:163], v[224:225]
	v_pk_fma_f32 v[94:95], v[94:95], v[160:161], v[222:223]
	global_store_dwordx4 v211, v[94:97], s[0:1]
	s_nop 1
	global_load_dwordx4 v[94:97], v197, s[0:1] offset:512 nt
	s_waitcnt vmcnt(19)
	v_pk_fma_f32 v[104:105], v[104:105], v[166:167], v[228:229]
	v_pk_fma_f32 v[102:103], v[102:103], v[164:165], v[226:227]
	global_store_dwordx4 v159, v[102:105], s[0:1] offset:64
	s_nop 1
	global_load_dwordx4 v[102:105], v234, s[0:1] offset:512 nt
	s_waitcnt vmcnt(20)
	v_pk_fma_f32 v[92:93], v[92:93], v[166:167], v[232:233]
	v_pk_fma_f32 v[90:91], v[90:91], v[164:165], v[230:231]
	global_store_dwordx4 v153, v[90:93], s[0:1] offset:64
	s_nop 1
	global_load_dwordx4 v[90:93], v235, s[0:1] offset:512 nt
	s_waitcnt vmcnt(21)
	v_pk_fma_f32 v[88:89], v[88:89], v[166:167], v[242:243]
	v_pk_fma_f32 v[86:87], v[86:87], v[164:165], v[240:241]
	global_store_dwordx4 v196, v[86:89], s[0:1] offset:64
	s_nop 1
	global_load_dwordx4 v[86:89], v210, s[0:1] offset:512 nt
	s_waitcnt vmcnt(22)
	v_pk_fma_f32 v[84:85], v[84:85], v[166:167], v[246:247]
	v_pk_fma_f32 v[82:83], v[82:83], v[164:165], v[244:245]
	global_store_dwordx4 v197, v[82:85], s[0:1] offset:64
	s_nop 1
	global_load_dwordx4 v[82:85], v211, s[0:1] offset:512 nt
	s_waitcnt vmcnt(22)
	v_pk_fma_f32 v[80:81], v[80:81], v[166:167], v[128:129]
	v_pk_fma_f32 v[78:79], v[78:79], v[164:165], v[126:127]
	global_store_dwordx4 v234, v[78:81], s[0:1] offset:64
	s_nop 1
	global_load_dwordx4 v[78:81], v159, s[0:1] offset:576 nt
	s_waitcnt vmcnt(22)
	v_pk_fma_f32 v[76:77], v[76:77], v[166:167], v[124:125]
	v_pk_fma_f32 v[74:75], v[74:75], v[164:165], v[122:123]
	global_store_dwordx4 v235, v[74:77], s[0:1] offset:64
	s_nop 1
	global_load_dwordx4 v[74:77], v153, s[0:1] offset:576 nt
	s_waitcnt vmcnt(22)
	v_pk_fma_f32 v[72:73], v[72:73], v[166:167], v[120:121]
	v_pk_fma_f32 v[70:71], v[70:71], v[164:165], v[118:119]
	global_store_dwordx4 v210, v[70:73], s[0:1] offset:64
	s_nop 1
	global_load_dwordx4 v[70:73], v196, s[0:1] offset:576 nt
	s_waitcnt vmcnt(22)
	v_pk_fma_f32 v[68:69], v[68:69], v[166:167], v[116:117]
	v_pk_fma_f32 v[66:67], v[66:67], v[164:165], v[114:115]
	global_store_dwordx4 v211, v[66:69], s[0:1] offset:64
	s_nop 1
	global_load_dwordx4 v[66:69], v197, s[0:1] offset:576 nt
	s_waitcnt vmcnt(22)
	v_pk_fma_f32 v[64:65], v[64:65], v[170:171], v[112:113]
	v_pk_fma_f32 v[62:63], v[62:63], v[168:169], v[110:111]
	global_store_dwordx4 v159, v[62:65], s[0:1] offset:512
	s_nop 1
	global_load_dwordx4 v[62:65], v234, s[0:1] offset:576 nt
	s_waitcnt vmcnt(22)
	v_pk_fma_f32 v[60:61], v[60:61], v[170:171], v[108:109]
	v_pk_fma_f32 v[58:59], v[58:59], v[168:169], v[106:107]
	global_store_dwordx4 v153, v[58:61], s[0:1] offset:512
	s_nop 1
	global_load_dwordx4 v[58:61], v235, s[0:1] offset:576 nt
	s_waitcnt vmcnt(22)
	v_pk_fma_f32 v[56:57], v[56:57], v[170:171], v[100:101]
	v_pk_fma_f32 v[54:55], v[54:55], v[168:169], v[98:99]
	global_store_dwordx4 v196, v[54:57], s[0:1] offset:512
	s_nop 1
	global_load_dwordx4 v[54:57], v210, s[0:1] offset:576 nt
	s_waitcnt vmcnt(22)
	v_pk_fma_f32 v[52:53], v[52:53], v[170:171], v[96:97]
	v_pk_fma_f32 v[50:51], v[50:51], v[168:169], v[94:95]
	global_store_dwordx4 v197, v[50:53], s[0:1] offset:512
	s_nop 1
	global_load_dwordx4 v[50:53], v211, s[0:1] offset:576 nt
	s_waitcnt vmcnt(22)
	v_pk_fma_f32 v[48:49], v[48:49], v[170:171], v[104:105]
	v_pk_fma_f32 v[46:47], v[46:47], v[168:169], v[102:103]
	global_store_dwordx4 v234, v[46:49], s[0:1] offset:512
	s_waitcnt vmcnt(21)
	v_pk_fma_f32 v[44:45], v[44:45], v[170:171], v[92:93]
	v_pk_fma_f32 v[42:43], v[42:43], v[168:169], v[90:91]
	global_store_dwordx4 v235, v[42:45], s[0:1] offset:512
	s_waitcnt vmcnt(20)
	v_pk_fma_f32 v[36:37], v[36:37], v[170:171], v[88:89]
	v_pk_fma_f32 v[34:35], v[34:35], v[168:169], v[86:87]
	global_store_dwordx4 v210, v[34:37], s[0:1] offset:512
	s_waitcnt vmcnt(19)
	v_pk_fma_f32 v[32:33], v[32:33], v[170:171], v[84:85]
	v_pk_fma_f32 v[30:31], v[30:31], v[168:169], v[82:83]
	global_store_dwordx4 v211, v[30:33], s[0:1] offset:512
	s_waitcnt vmcnt(18)
	v_pk_fma_f32 v[40:41], v[40:41], v[174:175], v[80:81]
	v_pk_fma_f32 v[38:39], v[38:39], v[172:173], v[78:79]
	global_store_dwordx4 v159, v[38:41], s[0:1] offset:576
	s_waitcnt vmcnt(17)
	v_pk_fma_f32 v[28:29], v[28:29], v[174:175], v[76:77]
	v_pk_fma_f32 v[26:27], v[26:27], v[172:173], v[74:75]
	global_store_dwordx4 v153, v[26:29], s[0:1] offset:576
	s_waitcnt vmcnt(16)
	v_pk_fma_f32 v[24:25], v[24:25], v[174:175], v[72:73]
	v_pk_fma_f32 v[22:23], v[22:23], v[172:173], v[70:71]
	global_store_dwordx4 v196, v[22:25], s[0:1] offset:576
	s_waitcnt vmcnt(15)
	v_pk_fma_f32 v[20:21], v[20:21], v[174:175], v[68:69]
	v_pk_fma_f32 v[18:19], v[18:19], v[172:173], v[66:67]
	global_store_dwordx4 v197, v[18:21], s[0:1] offset:576
	s_waitcnt vmcnt(14)
	v_pk_fma_f32 v[16:17], v[16:17], v[174:175], v[64:65]
	v_pk_fma_f32 v[14:15], v[14:15], v[172:173], v[62:63]
	global_store_dwordx4 v234, v[14:17], s[0:1] offset:576
	s_waitcnt vmcnt(13)
	v_pk_fma_f32 v[12:13], v[12:13], v[174:175], v[60:61]
	v_pk_fma_f32 v[10:11], v[10:11], v[172:173], v[58:59]
	global_store_dwordx4 v235, v[10:13], s[0:1] offset:576
	s_waitcnt vmcnt(12)
	v_pk_fma_f32 v[8:9], v[8:9], v[174:175], v[56:57]
	v_pk_fma_f32 v[6:7], v[6:7], v[172:173], v[54:55]
	global_store_dwordx4 v210, v[6:9], s[0:1] offset:576
	s_waitcnt vmcnt(11)
	v_pk_fma_f32 v[4:5], v[4:5], v[174:175], v[52:53]
	v_pk_fma_f32 v[2:3], v[2:3], v[172:173], v[50:51]
	global_store_dwordx4 v211, v[2:5], s[0:1] offset:576
	s_cbranch_vccnz .LBB0_1014
	s_andn2_b64 vcc, exec, s[40:41]
	s_cbranch_vccnz .LBB0_1013
	s_barrier
	s_branch .LBB0_1013

.LBB0_1250:
	s_sub_i32 s0, s37, 64
	s_ashr_i32 s1, s37, 31
	s_cmp_lt_i32 s37, 64
	s_cselect_b32 s1, s1, 0
	s_cselect_b32 s0, s37, s0
	s_movk_i32 s8, 0x4800
	s_cselect_b32 s2, s79, s97
	s_cselect_b32 s3, s78, s96
	s_cselect_b32 s8, 0x2400, s8
	s_lshl_b64 s[0:1], s[0:1], 20
	s_add_u32 s0, s3, s0
	s_addc_u32 s1, s2, s1
	s_cmp_gt_i32 s37, 31
	s_cselect_b32 s2, s8, 0
	s_lshl_b32 s2, s2, 2
	v_lshl_or_b32 v152, s36, 8, v157
	s_add_u32 s2, s29, s2
	v_ashrrev_i32_e32 v153, 31, v152
	s_addc_u32 s3, s30, 0
	v_lshlrev_b64 v[152:153], 2, v[152:153]
	global_load_dwordx4 v[160:163], v152, s[2:3]
	global_load_dwordx4 v[164:167], v152, s[2:3] offset:64
	global_load_dwordx4 v[168:171], v152, s[2:3] offset:512
	global_load_dwordx4 v[172:175], v152, s[2:3] offset:576
	v_add_u32_e32 v159, v152, v132
	v_add_u32_e32 v153, v152, v136
	v_add_u32_e32 v196, v152, v138
	v_add_u32_e32 v197, v152, v140
	v_add_u32_e32 v234, v152, v134
	v_add_u32_e32 v235, v152, v142
	v_add_u32_e32 v210, v152, v144
	v_add_u32_e32 v211, v152, v146
	global_load_dwordx4 v[176:179], v159, s[0:1] nt
	global_load_dwordx4 v[180:183], v153, s[0:1] nt
	global_load_dwordx4 v[184:187], v196, s[0:1] nt
	global_load_dwordx4 v[188:191], v197, s[0:1] nt
	global_load_dwordx4 v[192:195], v234, s[0:1] nt
	global_load_dwordx4 v[214:217], v235, s[0:1] nt
	global_load_dwordx4 v[218:221], v210, s[0:1] nt
	global_load_dwordx4 v[222:225], v211, s[0:1] nt
	global_load_dwordx4 v[226:229], v159, s[0:1] offset:64 nt
	global_load_dwordx4 v[230:233], v153, s[0:1] offset:64 nt
	global_load_dwordx4 v[240:243], v196, s[0:1] offset:64 nt
	global_load_dwordx4 v[244:247], v197, s[0:1] offset:64 nt
	v_readlane_b32 s18, v249, 56
	s_mov_b64 s[2:3], -1
	s_and_b64 vcc, exec, s[38:39]
	v_readlane_b32 s19, v249, 57
	s_waitcnt vmcnt(11)
	v_pk_mul_f32 v[160:161], v[160:161], 0.5 op_sel_hi:[1,0]
	v_pk_mul_f32 v[162:163], v[162:163], 0.5 op_sel_hi:[1,0]
	v_pk_fma_f32 v[128:129], v[128:129], v[162:163], v[178:179]
	v_pk_fma_f32 v[126:127], v[126:127], v[160:161], v[176:177]
	global_store_dwordx4 v159, v[126:129], s[0:1]
	s_nop 1
	global_load_dwordx4 v[126:129], v234, s[0:1] offset:64 nt
	s_waitcnt vmcnt(12)
	v_pk_fma_f32 v[124:125], v[124:125], v[162:163], v[182:183]
	v_pk_fma_f32 v[122:123], v[122:123], v[160:161], v[180:181]
	global_store_dwordx4 v153, v[122:125], s[0:1]
	s_nop 1
	global_load_dwordx4 v[122:125], v235, s[0:1] offset:64 nt
	s_waitcnt vmcnt(13)
	v_pk_fma_f32 v[120:121], v[120:121], v[162:163], v[186:187]
	v_pk_fma_f32 v[118:119], v[118:119], v[160:161], v[184:185]
	global_store_dwordx4 v196, v[118:121], s[0:1]
	s_nop 1
	global_load_dwordx4 v[118:121], v210, s[0:1] offset:64 nt
	s_waitcnt vmcnt(14)
	v_pk_fma_f32 v[116:117], v[116:117], v[162:163], v[190:191]
	v_pk_fma_f32 v[114:115], v[114:115], v[160:161], v[188:189]
	global_store_dwordx4 v197, v[114:117], s[0:1]
	s_nop 1
	global_load_dwordx4 v[114:117], v211, s[0:1] offset:64 nt
	s_waitcnt vmcnt(15)
	v_pk_fma_f32 v[112:113], v[112:113], v[162:163], v[194:195]
	v_pk_fma_f32 v[110:111], v[110:111], v[160:161], v[192:193]
	global_store_dwordx4 v234, v[110:113], s[0:1]
	s_nop 1
	global_load_dwordx4 v[110:113], v159, s[0:1] offset:512 nt
	s_waitcnt vmcnt(16)
	v_pk_fma_f32 v[108:109], v[108:109], v[162:163], v[216:217]
	v_pk_fma_f32 v[106:107], v[106:107], v[160:161], v[214:215]
	global_store_dwordx4 v235, v[106:109], s[0:1]
	s_nop 1
	global_load_dwordx4 v[106:109], v153, s[0:1] offset:512 nt
	s_waitcnt vmcnt(17)
	v_pk_fma_f32 v[104:105], v[104:105], v[162:163], v[220:221]
	v_pk_fma_f32 v[102:103], v[102:103], v[160:161], v[218:219]
	global_store_dwordx4 v210, v[102:105], s[0:1]
	s_nop 1
	global_load_dwordx4 v[102:105], v196, s[0:1] offset:512 nt
	s_waitcnt vmcnt(18)
	v_pk_fma_f32 v[96:97], v[96:97], v[162:163], v[224:225]
	v_pk_fma_f32 v[94:95], v[94:95], v[160:161], v[222:223]
	global_store_dwordx4 v211, v[94:97], s[0:1]
	s_nop 1
	global_load_dwordx4 v[94:97], v197, s[0:1] offset:512 nt
	s_waitcnt vmcnt(19)
	v_pk_mul_f32 v[164:165], v[164:165], 0.5 op_sel_hi:[1,0]
	v_pk_mul_f32 v[166:167], v[166:167], 0.5 op_sel_hi:[1,0]
	v_pk_fma_f32 v[100:101], v[100:101], v[166:167], v[228:229]
	v_pk_fma_f32 v[98:99], v[98:99], v[164:165], v[226:227]
	global_store_dwordx4 v159, v[98:101], s[0:1] offset:64
	s_nop 1
	global_load_dwordx4 v[98:101], v234, s[0:1] offset:512 nt
	s_waitcnt vmcnt(20)
	v_pk_fma_f32 v[92:93], v[92:93], v[166:167], v[232:233]
	v_pk_fma_f32 v[90:91], v[90:91], v[164:165], v[230:231]
	global_store_dwordx4 v153, v[90:93], s[0:1] offset:64
	s_nop 1
	global_load_dwordx4 v[90:93], v235, s[0:1] offset:512 nt
	s_waitcnt vmcnt(21)
	v_pk_fma_f32 v[88:89], v[88:89], v[166:167], v[242:243]
	v_pk_fma_f32 v[86:87], v[86:87], v[164:165], v[240:241]
	global_store_dwordx4 v196, v[86:89], s[0:1] offset:64
	s_nop 1
	global_load_dwordx4 v[86:89], v210, s[0:1] offset:512 nt
	s_waitcnt vmcnt(22)
	v_pk_fma_f32 v[84:85], v[84:85], v[166:167], v[246:247]
	v_pk_fma_f32 v[82:83], v[82:83], v[164:165], v[244:245]
	global_store_dwordx4 v197, v[82:85], s[0:1] offset:64
	s_nop 1
	global_load_dwordx4 v[82:85], v211, s[0:1] offset:512 nt
	s_waitcnt vmcnt(22)
	v_pk_fma_f32 v[80:81], v[80:81], v[166:167], v[128:129]
	v_pk_fma_f32 v[78:79], v[78:79], v[164:165], v[126:127]
	global_store_dwordx4 v234, v[78:81], s[0:1] offset:64
	s_nop 1
	global_load_dwordx4 v[78:81], v159, s[0:1] offset:576 nt
	s_waitcnt vmcnt(22)
	v_pk_fma_f32 v[76:77], v[76:77], v[166:167], v[124:125]
	v_pk_fma_f32 v[74:75], v[74:75], v[164:165], v[122:123]
	global_store_dwordx4 v235, v[74:77], s[0:1] offset:64
	s_nop 1
	global_load_dwordx4 v[74:77], v153, s[0:1] offset:576 nt
	s_waitcnt vmcnt(22)
	v_pk_fma_f32 v[72:73], v[72:73], v[166:167], v[120:121]
	v_pk_fma_f32 v[70:71], v[70:71], v[164:165], v[118:119]
	global_store_dwordx4 v210, v[70:73], s[0:1] offset:64
	s_nop 1
	global_load_dwordx4 v[70:73], v196, s[0:1] offset:576 nt
	s_waitcnt vmcnt(22)
	v_pk_fma_f32 v[64:65], v[64:65], v[166:167], v[116:117]
	v_pk_fma_f32 v[62:63], v[62:63], v[164:165], v[114:115]
	global_store_dwordx4 v211, v[62:65], s[0:1] offset:64
	s_nop 1
	global_load_dwordx4 v[62:65], v197, s[0:1] offset:576 nt
	s_waitcnt vmcnt(22)
	v_pk_mul_f32 v[168:169], v[168:169], 0.5 op_sel_hi:[1,0]
	v_pk_mul_f32 v[170:171], v[170:171], 0.5 op_sel_hi:[1,0]
	v_pk_fma_f32 v[68:69], v[68:69], v[170:171], v[112:113]
	v_pk_fma_f32 v[66:67], v[66:67], v[168:169], v[110:111]
	global_store_dwordx4 v159, v[66:69], s[0:1] offset:512
	s_nop 1
	global_load_dwordx4 v[66:69], v234, s[0:1] offset:576 nt
	s_waitcnt vmcnt(22)
	v_pk_fma_f32 v[60:61], v[60:61], v[170:171], v[108:109]
	v_pk_fma_f32 v[58:59], v[58:59], v[168:169], v[106:107]
	global_store_dwordx4 v153, v[58:61], s[0:1] offset:512
	s_nop 1
	global_load_dwordx4 v[58:61], v235, s[0:1] offset:576 nt
	s_waitcnt vmcnt(22)
	v_pk_fma_f32 v[56:57], v[56:57], v[170:171], v[104:105]
	v_pk_fma_f32 v[54:55], v[54:55], v[168:169], v[102:103]
	global_store_dwordx4 v196, v[54:57], s[0:1] offset:512
	s_nop 1
	global_load_dwordx4 v[54:57], v210, s[0:1] offset:576 nt
	s_waitcnt vmcnt(22)
	v_pk_fma_f32 v[52:53], v[52:53], v[170:171], v[96:97]
	v_pk_fma_f32 v[50:51], v[50:51], v[168:169], v[94:95]
	global_store_dwordx4 v197, v[50:53], s[0:1] offset:512
	s_nop 1
	global_load_dwordx4 v[50:53], v211, s[0:1] offset:576 nt
	s_waitcnt vmcnt(22)
	v_pk_fma_f32 v[48:49], v[48:49], v[170:171], v[100:101]
	v_pk_fma_f32 v[46:47], v[46:47], v[168:169], v[98:99]
	global_store_dwordx4 v234, v[46:49], s[0:1] offset:512
	s_waitcnt vmcnt(21)
	v_pk_fma_f32 v[44:45], v[44:45], v[170:171], v[92:93]
	v_pk_fma_f32 v[42:43], v[42:43], v[168:169], v[90:91]
	global_store_dwordx4 v235, v[42:45], s[0:1] offset:512
	s_waitcnt vmcnt(20)
	v_pk_fma_f32 v[40:41], v[40:41], v[170:171], v[88:89]
	v_pk_fma_f32 v[38:39], v[38:39], v[168:169], v[86:87]
	global_store_dwordx4 v210, v[38:41], s[0:1] offset:512
	s_waitcnt vmcnt(19)
	v_pk_fma_f32 v[32:33], v[32:33], v[170:171], v[84:85]
	v_pk_fma_f32 v[30:31], v[30:31], v[168:169], v[82:83]
	global_store_dwordx4 v211, v[30:33], s[0:1] offset:512
	s_waitcnt vmcnt(18)
	v_pk_mul_f32 v[172:173], v[172:173], 0.5 op_sel_hi:[1,0]
	v_pk_mul_f32 v[174:175], v[174:175], 0.5 op_sel_hi:[1,0]
	v_pk_fma_f32 v[36:37], v[36:37], v[174:175], v[80:81]
	v_pk_fma_f32 v[34:35], v[34:35], v[172:173], v[78:79]
	global_store_dwordx4 v159, v[34:37], s[0:1] offset:576
	s_waitcnt vmcnt(17)
	v_pk_fma_f32 v[28:29], v[28:29], v[174:175], v[76:77]
	v_pk_fma_f32 v[26:27], v[26:27], v[172:173], v[74:75]
	global_store_dwordx4 v153, v[26:29], s[0:1] offset:576
	s_waitcnt vmcnt(16)
	v_pk_fma_f32 v[24:25], v[24:25], v[174:175], v[72:73]
	v_pk_fma_f32 v[22:23], v[22:23], v[172:173], v[70:71]
	global_store_dwordx4 v196, v[22:25], s[0:1] offset:576
	s_waitcnt vmcnt(15)
	v_pk_fma_f32 v[20:21], v[20:21], v[174:175], v[64:65]
	v_pk_fma_f32 v[18:19], v[18:19], v[172:173], v[62:63]
	global_store_dwordx4 v197, v[18:21], s[0:1] offset:576
	s_waitcnt vmcnt(14)
	v_pk_fma_f32 v[16:17], v[16:17], v[174:175], v[68:69]
	v_pk_fma_f32 v[14:15], v[14:15], v[172:173], v[66:67]
	global_store_dwordx4 v234, v[14:17], s[0:1] offset:576
	s_waitcnt vmcnt(13)
	v_pk_fma_f32 v[12:13], v[12:13], v[174:175], v[60:61]
	v_pk_fma_f32 v[10:11], v[10:11], v[172:173], v[58:59]
	global_store_dwordx4 v235, v[10:13], s[0:1] offset:576
	s_waitcnt vmcnt(12)
	v_pk_fma_f32 v[8:9], v[8:9], v[174:175], v[56:57]
	v_pk_fma_f32 v[6:7], v[6:7], v[172:173], v[54:55]
	global_store_dwordx4 v210, v[6:9], s[0:1] offset:576
	s_waitcnt vmcnt(11)
	v_pk_fma_f32 v[4:5], v[4:5], v[174:175], v[52:53]
	v_pk_fma_f32 v[2:3], v[2:3], v[172:173], v[50:51]
	global_store_dwordx4 v211, v[2:5], s[0:1] offset:576
	s_cbranch_vccnz .LBB0_1235
	s_andn2_b64 vcc, exec, s[42:43]
	s_cbranch_vccnz .LBB0_1234
	s_barrier
	s_branch .LBB0_1234
